# v18: v16 with the loop-exit row-sum transposition moved to private LDS scratch above the parked O (removes a latent LDS overlap with other waves' output staging)
# speedup vs baseline: 1.0111x; 1.0033x over previous
.Lfo_out_c1:
	v_mov_b32_e32 v241, v239
	s_nop 1
	v_permlane32_swap_b32_e32 v239, v241
	v_add_f32_e32 v239, v239, v241
	v_add_u32_e32 v241, 0x12800, v174
	ds_write_b32 v241, v239 offset:59392
	v_add_u32_e32 v240, s91, v172
	v_add_u32_e32 v240, 0x12800, v240
	s_waitcnt lgkmcnt(0)
	ds_read_b128 v[66:69], v240 offset:59392
	ds_read_b128 v[70:73], v240 offset:59424
	ds_read_b128 v[74:77], v240 offset:59456
	ds_read_b128 v[78:81], v240 offset:59488
	s_waitcnt lgkmcnt(0)
	s_branch .LBB0_49

.Lfo_out_c2:
	v_mov_b32_e32 v155, v238
	s_nop 1
	v_permlane32_swap_b32_e32 v238, v155
	v_add_f32_e32 v238, v238, v155
	v_add_u32_e32 v155, 0x12800, v174
	ds_write_b32 v155, v238 offset:59392
	v_add_u32_e32 v154, s91, v172
	v_add_u32_e32 v154, 0x12800, v154
	s_waitcnt lgkmcnt(0)
	ds_read_b128 v[66:69], v154 offset:59392
	ds_read_b128 v[70:73], v154 offset:59424
	ds_read_b128 v[74:77], v154 offset:59456
	ds_read_b128 v[78:81], v154 offset:59488
	s_waitcnt lgkmcnt(0)
	s_branch .LBB0_64

.Lfo_out_c3:
	v_mov_b32_e32 v191, v243
	s_nop 1
	v_permlane32_swap_b32_e32 v243, v191
	v_add_f32_e32 v243, v243, v191
	v_add_u32_e32 v191, 0x12800, v180
	ds_write_b32 v191, v243 offset:59392
	v_add_u32_e32 v190, s91, v178
	v_add_u32_e32 v190, 0x12800, v190
	s_waitcnt lgkmcnt(0)
	ds_read_b128 v[66:69], v190 offset:59392
	ds_read_b128 v[70:73], v190 offset:59424
	ds_read_b128 v[74:77], v190 offset:59456
	ds_read_b128 v[78:81], v190 offset:59488
	s_waitcnt lgkmcnt(0)
	s_branch .LBB0_79

.Lfo_out_c4:
	v_mov_b32_e32 v155, v238
	s_nop 1
	v_permlane32_swap_b32_e32 v238, v155
	v_add_f32_e32 v238, v238, v155
	v_add_u32_e32 v155, 0x12800, v180
	ds_write_b32 v155, v238 offset:59392
	v_add_u32_e32 v154, s91, v178
	v_add_u32_e32 v154, 0x12800, v154
	s_waitcnt lgkmcnt(0)
	ds_read_b128 v[66:69], v154 offset:59392
	ds_read_b128 v[70:73], v154 offset:59424
	ds_read_b128 v[74:77], v154 offset:59456
	ds_read_b128 v[78:81], v154 offset:59488
	s_waitcnt lgkmcnt(0)
	s_branch .LBB0_33
